# post phase: yraw loads for the next 8-group batch software-prefetched into a second register set (hides one memory latency per batch)
# baseline (speedup 1.0000x reference)
.LBB0_169:
	v_ashrrev_i32_e32 v53, 31, v52
	v_lshlrev_b64 v[56:57], 11, v[52:53]
	v_lshlrev_b64 v[58:59], 10, v[52:53]
	v_or_b32_e32 v56, v44, v56
	v_or_b32_e32 v58, v54, v58
	s_add_u32 s100, s84, 0x18800000
	s_addc_u32 s101, s85, 0
	global_load_dwordx4 v[100:103], v58, s[100:101]
	global_load_dwordx4 v[104:107], v58, s[100:101] offset:32
	global_load_dwordx4 v[108:111], v58, s[100:101] offset:64
	global_load_dwordx4 v[112:115], v58, s[100:101] offset:96
	global_load_dwordx4 v[116:119], v58, s[100:101] offset:128
	global_load_dwordx4 v[120:123], v58, s[100:101] offset:160
	global_load_dwordx4 v[124:127], v58, s[100:101] offset:192
	global_load_dwordx4 v[128:131], v58, s[100:101] offset:224
	s_mov_b64 s[6:7], -1
	v_mov_b32_e32 v53, 0
	v_mov_b32_e32 v70, 0
	s_branch .LBB0_171

.LBB0_173:
	ds_read_b128 v[74:77], v71
	s_waitcnt vmcnt(0)
	v_mov_b64_e32 v[0:1], v[100:101]
	v_mov_b64_e32 v[2:3], v[102:103]
	v_mov_b64_e32 v[40:41], v[104:105]
	v_mov_b64_e32 v[42:43], v[106:107]
	v_mov_b64_e32 v[36:37], v[108:109]
	v_mov_b64_e32 v[38:39], v[110:111]
	v_mov_b64_e32 v[32:33], v[112:113]
	v_mov_b64_e32 v[34:35], v[114:115]
	v_mov_b64_e32 v[28:29], v[116:117]
	v_mov_b64_e32 v[30:31], v[118:119]
	v_mov_b64_e32 v[24:25], v[120:121]
	v_mov_b64_e32 v[26:27], v[122:123]
	v_mov_b64_e32 v[20:21], v[124:125]
	v_mov_b64_e32 v[22:23], v[126:127]
	v_mov_b64_e32 v[16:17], v[128:129]
	v_mov_b64_e32 v[18:19], v[130:131]
	s_add_u32 s100, s10, 0x18800100
	s_addc_u32 s101, s11, 0
	s_cmp_eq_u32 s14, 16
	s_cbranch_scc0 .Lpp_nowrap
	s_add_u32 s100, s84, 0x18800000
	s_addc_u32 s101, s85, 0
.Lpp_nowrap:
	global_load_dwordx4 v[100:103], v58, s[100:101]
	global_load_dwordx4 v[104:107], v58, s[100:101] offset:32
	global_load_dwordx4 v[108:111], v58, s[100:101] offset:64
	global_load_dwordx4 v[112:115], v58, s[100:101] offset:96
	global_load_dwordx4 v[116:119], v58, s[100:101] offset:128
	global_load_dwordx4 v[120:123], v58, s[100:101] offset:160
	global_load_dwordx4 v[124:127], v58, s[100:101] offset:192
	global_load_dwordx4 v[128:131], v58, s[100:101] offset:224
	s_mov_b64 s[4:5], -1
	s_and_b64 vcc, exec, s[8:9]
	v_lshl_add_u64 v[60:61], s[10:11], 0, v[56:57]
	s_waitcnt lgkmcnt(0)
	v_lshlrev_b32_e32 v4, 16, v0
	v_and_b32_e32 v0, 0xffff0000, v0
	v_lshlrev_b32_e32 v5, 16, v1
	v_and_b32_e32 v1, 0xffff0000, v1
	v_lshlrev_b32_e32 v6, 16, v2
	v_and_b32_e32 v2, 0xffff0000, v2
	v_lshlrev_b32_e32 v7, 16, v3
	v_and_b32_e32 v3, 0xffff0000, v3
	v_mul_f32_e32 v8, 0x3d372713, v4
	v_mul_f32_e32 v9, 0x3d372713, v0
	v_mul_f32_e32 v10, 0x3d372713, v5
	v_mul_f32_e32 v11, 0x3d372713, v1
	v_mul_f32_e32 v12, 0x3d372713, v6
	v_mul_f32_e32 v13, 0x3d372713, v2
	v_mul_f32_e32 v14, 0x3d372713, v7
	v_mul_f32_e32 v15, 0x3d372713, v3
	v_mul_f32_e32 v8, v8, v4
	v_mul_f32_e32 v9, v9, v0
	v_mul_f32_e32 v10, v10, v5
	v_mul_f32_e32 v11, v11, v1
	v_mul_f32_e32 v12, v12, v6
	v_mul_f32_e32 v13, v13, v2
	v_mul_f32_e32 v14, v14, v7
	v_mul_f32_e32 v15, v15, v3
	v_fma_f32 v8, v8, v4, v4
	v_fma_f32 v9, v9, v0, v0
	v_fma_f32 v10, v10, v5, v5
	v_fma_f32 v11, v11, v1, v1
	v_fma_f32 v12, v12, v6, v6
	v_fma_f32 v13, v13, v2, v2
	v_fma_f32 v14, v14, v7, v7
	v_fma_f32 v15, v15, v3, v3
	v_mul_f32_e32 v8, 0x3fcc422a, v8
	v_mul_f32_e32 v9, 0x3fcc422a, v9
	v_mul_f32_e32 v10, 0x3fcc422a, v10
	v_mul_f32_e32 v11, 0x3fcc422a, v11
	v_mul_f32_e32 v12, 0x3fcc422a, v12
	v_mul_f32_e32 v13, 0x3fcc422a, v13
	v_mul_f32_e32 v14, 0x3fcc422a, v14
	v_mul_f32_e32 v15, 0x3fcc422a, v15
	v_mul_f32_e32 v8, 0xbfb8aa3b, v8
	v_mul_f32_e32 v9, 0xbfb8aa3b, v9
	v_mul_f32_e32 v10, 0xbfb8aa3b, v10
	v_mul_f32_e32 v11, 0xbfb8aa3b, v11
	v_mul_f32_e32 v12, 0xbfb8aa3b, v12
	v_mul_f32_e32 v13, 0xbfb8aa3b, v13
	v_mul_f32_e32 v14, 0xbfb8aa3b, v14
	v_mul_f32_e32 v15, 0xbfb8aa3b, v15
	v_exp_f32_e32 v8, v8
	v_exp_f32_e32 v9, v9
	v_exp_f32_e32 v10, v10
	v_exp_f32_e32 v11, v11
	v_exp_f32_e32 v12, v12
	v_exp_f32_e32 v13, v13
	v_exp_f32_e32 v14, v14
	v_exp_f32_e32 v15, v15
	v_add_f32_e32 v8, 1.0, v8
	v_add_f32_e32 v9, 1.0, v9
	v_add_f32_e32 v10, 1.0, v10
	v_add_f32_e32 v11, 1.0, v11
	v_add_f32_e32 v12, 1.0, v12
	v_add_f32_e32 v13, 1.0, v13
	v_add_f32_e32 v14, 1.0, v14
	v_add_f32_e32 v15, 1.0, v15
	v_rcp_f32_e32 v8, v8
	v_rcp_f32_e32 v9, v9
	v_rcp_f32_e32 v10, v10
	v_rcp_f32_e32 v11, v11
	v_rcp_f32_e32 v12, v12
	v_rcp_f32_e32 v13, v13
	v_rcp_f32_e32 v14, v14
	v_rcp_f32_e32 v15, v15
	v_mul_f32_e32 v4, v8, v4
	v_mul_f32_e32 v0, v9, v0
	v_mul_f32_e32 v5, v10, v5
	v_mul_f32_e32 v1, v11, v1
	v_mul_f32_e32 v6, v12, v6
	v_mul_f32_e32 v2, v13, v2
	v_mul_f32_e32 v7, v14, v7
	v_mul_f32_e32 v3, v15, v3
	v_cvt_pk_bf16_f32 v78, v4, v0
	v_cvt_pk_bf16_f32 v79, v5, v1
	v_cvt_pk_bf16_f32 v80, v6, v2
	v_cvt_pk_bf16_f32 v81, v7, v3
	ds_read_b128 v[0:3], v72
	ds_read_b128 v[4:7], v72 offset:32
	ds_read_b128 v[8:11], v72 offset:64
	ds_read_b128 v[12:15], v72 offset:96
	s_nop 4
	s_waitcnt lgkmcnt(0)
	v_mfma_f32_32x32x16_bf16 v[0:15], v[74:77], v[78:81], v[0:15]
	s_nop 11
	v_mul_f32_e32 v11, 0xbfb8aa3b, v11
	v_mul_f32_e32 v8, 0xbfb8aa3b, v8
	v_mul_f32_e32 v9, 0xbfb8aa3b, v9
	v_mul_f32_e32 v10, 0xbfb8aa3b, v10
	v_exp_f32_e32 v11, v11
	v_exp_f32_e32 v8, v8
	v_exp_f32_e32 v9, v9
	v_exp_f32_e32 v10, v10
	v_add_f32_e32 v11, 1.0, v11
	v_add_f32_e32 v8, 1.0, v8
	v_add_f32_e32 v9, 1.0, v9
	v_add_f32_e32 v10, 1.0, v10
	v_rcp_f32_e32 v11, v11
	v_rcp_f32_e32 v8, v8
	v_rcp_f32_e32 v9, v9
	v_rcp_f32_e32 v10, v10
	v_mul_f32_e32 v3, v3, v11
	v_mul_f32_e32 v0, v0, v8
	v_mul_f32_e32 v1, v1, v9
	v_mul_f32_e32 v2, v2, v10
	v_cvt_pk_bf16_f32 v8, v0, v1
	v_cvt_pk_bf16_f32 v3, v2, v3
	s_nop 0
	v_lshlrev_b32_e32 v0, 16, v8
	v_lshlrev_b32_e32 v1, 16, v3
	v_and_b32_e32 v2, 0xffff0000, v8
	v_and_b32_e32 v3, 0xffff0000, v3
	s_cbranch_vccz .LBB0_175
	ds_read_b128 v[8:11], v73
	v_mul_f32_e32 v74, v70, v0
	s_mov_b64 s[4:5], 0
	s_waitcnt lgkmcnt(0)
	v_mul_f32_e32 v8, v74, v8
	v_mul_f32_e32 v74, v70, v2
	v_mul_f32_e32 v9, v74, v9
	v_cvt_pk_bf16_f32 v8, v8, v9
	v_mul_f32_e32 v9, v70, v1
	v_mul_f32_e32 v9, v9, v10
	v_mul_f32_e32 v10, v70, v3
	v_mul_f32_e32 v10, v10, v11
	v_cvt_pk_bf16_f32 v9, v9, v10
	v_add_co_u32_e32 v10, vcc, 0x10800000, v60
	s_nop 1
	v_addc_co_u32_e32 v11, vcc, 0, v61, vcc
	global_store_dwordx2 v[10:11], v[8:9], off
